# FINAL-norm loop: both batches of rms partial-sum loads issued together (one load latency less per iteration)
# speedup vs baseline: 1.0010x; 1.0010x over previous
; DI int tidx() { int t = __builtin_amdgcn_workitem_id_x(); asm volatile("" : "+v"(t)); return t; }
; DI float bflo(unsigned u) { return __uint_as_float(u << 16); }
; DI float bfhi(unsigned u) { return __uint_as_float(u & 0xffff0000u); }
; DI float rstd16(const float* ssq, int m) {
;   float s = 0.f;
; #pragma unroll
;   for (int c = 0; c < 16; ++c) s += ssq[(size_t)c * TP + m];
;   return rsqrtf(s * (1.f / 1024.f) + RMS_EPS);
; }
; DI void final_rows(CP p, int item) {
;   const int lane = tidx() & 63, wv = tidx() >> 6;
;   const int orow = item * 8 + wv;
;   int r;
;   if (orow < 16384) { int s = orow >> 13; r = s * LPR + 16 + (orow & 8191); }
;   else { int x = orow - 16384; int s = x >> 11; r = 2 * LPR + s * LSM + 16 + (x & 2047); }
;   const float rs = rstd16(p.ssq, r);
;   const u16* src = p.hb + (size_t)r * 1024 + lane * 16;
;   uint4 a = *(const uint4*)src, b = *(const uint4*)(src + 8);
;   unsigned w[8] = {a.x, a.y, a.z, a.w, b.x, b.y, b.z, b.w};
;   float* dst = p.out + (size_t)orow * 1024 + lane * 16;
;   const float* gn = p.final_norm + lane * 16;
; #pragma unroll
;   for (int i = 0; i < 4; ++i) {
;     float4 o;
;     o.x = bflo(w[2 * i]) * rs * gn[4 * i]; o.y = bfhi(w[2 * i]) * rs * gn[4 * i + 1];
;     o.z = bflo(w[2 * i + 1]) * rs * gn[4 * i + 2]; o.w = bfhi(w[2 * i + 1]) * rs * gn[4 * i + 3];
;     *(float4*)(dst + 4 * i) = o;
;   }
; }
.LBB0_14:
	s_or_b64 exec, exec, s[8:9]
	s_load_dwordx2 s[8:9], s[0:1], 0x128
	v_and_b32_e32 v5, v5, v2
	v_add3_u32 v4, v5, v4, v3
	v_ashrrev_i32_e32 v5, 31, v4
	v_lshlrev_b32_e32 v0, 4, v0
	s_waitcnt lgkmcnt(0)
	v_lshl_add_u64 v[6:7], v[4:5], 2, s[8:9]
	s_waitcnt vmcnt(2)
	v_add_co_u32_e32 v8, vcc, 0x20000, v6
	v_lshlrev_b64 v[4:5], 11, v[4:5]
	s_nop 0
	v_addc_co_u32_e32 v9, vcc, 0, v7, vcc
	v_add_co_u32_e32 v10, vcc, 0x40000, v6
	s_add_i32 s14, s14, s94
	s_nop 0
	v_addc_co_u32_e32 v11, vcc, 0, v7, vcc
	v_add_co_u32_e32 v12, vcc, 0x60000, v6
	s_add_i32 s11, s11, s10
	s_nop 0
	v_addc_co_u32_e32 v13, vcc, 0, v7, vcc
	v_add_co_u32_e32 v14, vcc, 0x81000, v6
	s_cmpk_gt_i32 s14, 0xfff
	s_nop 0
	v_addc_co_u32_e32 v15, vcc, 0, v7, vcc
	s_waitcnt vmcnt(1)
	v_add_co_u32_e32 v16, vcc, 0xa1000, v6
	s_nop 1
	v_addc_co_u32_e32 v17, vcc, 0, v7, vcc
	v_add_co_u32_e32 v18, vcc, 0xc1000, v6
	s_nop 1
	v_addc_co_u32_e32 v19, vcc, 0, v7, vcc
	s_waitcnt vmcnt(0)
	v_add_co_u32_e32 v20, vcc, 0xe1000, v6
	s_nop 1
	v_addc_co_u32_e32 v21, vcc, 0, v7, vcc
	global_load_dword v3, v[6:7], off
	global_load_dword v22, v[8:9], off offset:1024
	global_load_dword v23, v[10:11], off offset:2048
	global_load_dword v24, v[12:13], off offset:3072
	global_load_dword v25, v[14:15], off
	global_load_dword v26, v[16:17], off offset:1024
	global_load_dword v27, v[18:19], off offset:2048
	global_load_dword v28, v[20:21], off offset:3072
	v_add_co_u32_e32 v216, vcc, 0x102000, v6
	s_nop 1
	v_addc_co_u32_e32 v217, vcc, 0, v7, vcc
	v_add_co_u32_e32 v218, vcc, 0x122000, v6
	s_nop 1
	v_addc_co_u32_e32 v219, vcc, 0, v7, vcc
	v_add_co_u32_e32 v220, vcc, 0x142000, v6
	s_nop 1
	v_addc_co_u32_e32 v221, vcc, 0, v7, vcc
	v_add_co_u32_e32 v222, vcc, 0x162000, v6
	s_nop 1
	v_addc_co_u32_e32 v223, vcc, 0, v7, vcc
	v_add_co_u32_e32 v224, vcc, 0x183000, v6
	s_nop 1
	v_addc_co_u32_e32 v225, vcc, 0, v7, vcc
	v_add_co_u32_e32 v226, vcc, 0x1a3000, v6
	s_nop 1
	v_addc_co_u32_e32 v227, vcc, 0, v7, vcc
	v_add_co_u32_e32 v228, vcc, 0x1c3000, v6
	s_nop 1
	v_addc_co_u32_e32 v229, vcc, 0, v7, vcc
	v_add_co_u32_e32 v230, vcc, 0x1e3000, v6
	s_nop 1
	v_addc_co_u32_e32 v231, vcc, 0, v7, vcc
	global_load_dword v232, v[216:217], off
	global_load_dword v233, v[218:219], off offset:1024
	global_load_dword v234, v[220:221], off offset:2048
	global_load_dword v235, v[222:223], off offset:3072
	global_load_dword v240, v[224:225], off
	global_load_dword v241, v[226:227], off offset:1024
	global_load_dword v242, v[228:229], off offset:2048
	global_load_dword v243, v[230:231], off offset:3072
	s_waitcnt vmcnt(15)
	v_add_f32_e32 v3, 0, v3
	s_waitcnt vmcnt(14)
	v_add_f32_e32 v3, v3, v22
	s_waitcnt vmcnt(13)
	v_add_f32_e32 v3, v3, v23
	s_waitcnt vmcnt(12)
	v_add_f32_e32 v3, v3, v24
	s_waitcnt vmcnt(11)
	v_add_f32_e32 v3, v3, v25
	s_waitcnt vmcnt(10)
	v_add_f32_e32 v3, v3, v26
	s_waitcnt vmcnt(9)
	v_add_f32_e32 v3, v3, v27
	s_waitcnt vmcnt(8)
	v_add_f32_e32 v3, v3, v28
	s_load_dwordx2 s[8:9], s[0:1], 0xf8
	v_and_b32_e32 v8, 0x3f0, v0
	v_lshlrev_b32_e32 v0, 1, v8
	s_waitcnt lgkmcnt(0)
	v_lshl_add_u64 v[4:5], s[8:9], 0, v[4:5]
	v_lshl_add_u64 v[12:13], v[4:5], 0, v[0:1]
	global_load_dwordx4 v[4:7], v[12:13], off
	v_lshlrev_b32_e32 v0, 2, v8
	global_load_dwordx4 v[8:11], v0, s[40:41]
	global_load_dwordx4 v[200:203], v0, s[40:41] offset:16
	global_load_dwordx4 v[204:207], v0, s[40:41] offset:32
	global_load_dwordx4 v[208:211], v0, s[40:41] offset:48
	s_mov_b32 s8, 0x800000
	s_waitcnt vmcnt(12)
	v_add_f32_e32 v3, v3, v232
	s_waitcnt vmcnt(11)
	v_add_f32_e32 v3, v3, v233
	s_waitcnt vmcnt(10)
	v_add_f32_e32 v3, v3, v234
	s_waitcnt vmcnt(9)
	v_add_f32_e32 v3, v3, v235
	s_waitcnt vmcnt(8)
	v_add_f32_e32 v3, v3, v240
	s_waitcnt vmcnt(7)
	v_add_f32_e32 v3, v3, v241
	s_waitcnt vmcnt(6)
	v_add_f32_e32 v3, v3, v242
	s_waitcnt vmcnt(5)
	v_add_f32_e32 v3, v3, v243
	v_fmamk_f32 v3, v3, 0x3a800000, v180
	v_mul_f32_e32 v14, 0x4b800000, v3
	v_cmp_gt_f32_e32 vcc, s8, v3
	s_nop 1
	v_cndmask_b32_e32 v3, v3, v14, vcc
	v_rsq_f32_e32 v3, v3
	global_load_dwordx4 v[12:15], v[12:13], off offset:16
	v_mul_f32_e32 v16, 0x45800000, v3
	v_cndmask_b32_e32 v16, v3, v16, vcc
	v_ashrrev_i32_e32 v3, 31, v2
	v_lshlrev_b64 v[2:3], 12, v[2:3]
	v_lshl_add_u64 v[2:3], s[42:43], 0, v[2:3]
	v_lshl_add_u64 v[18:19], v[2:3], 0, v[0:1]
	s_waitcnt vmcnt(5)
	v_lshlrev_b32_e32 v2, 16, v4
	v_and_b32_e32 v3, 0xffff0000, v4
	v_lshlrev_b32_e32 v4, 16, v5
	v_and_b32_e32 v5, 0xffff0000, v5
	v_pk_mul_f32 v[2:3], v[16:17], v[2:3] op_sel_hi:[0,1]
	v_pk_mul_f32 v[4:5], v[16:17], v[4:5] op_sel_hi:[0,1]
	s_waitcnt vmcnt(4)
	v_pk_mul_f32 v[2:3], v[2:3], v[8:9]
	v_pk_mul_f32 v[4:5], v[4:5], v[10:11]
	global_store_dwordx4 v[18:19], v[2:5], off
	v_lshlrev_b32_e32 v8, 16, v6
	v_and_b32_e32 v9, 0xffff0000, v6
	v_lshlrev_b32_e32 v6, 16, v7
	v_and_b32_e32 v7, 0xffff0000, v7
	v_pk_mul_f32 v[8:9], v[16:17], v[8:9] op_sel_hi:[0,1]
	v_pk_mul_f32 v[6:7], v[16:17], v[6:7] op_sel_hi:[0,1]
	s_waitcnt vmcnt(1)
	v_pk_mul_f32 v[2:3], v[8:9], v[200:201]
	v_pk_mul_f32 v[4:5], v[6:7], v[202:203]
	global_store_dwordx4 v[18:19], v[2:5], off offset:16
	v_lshlrev_b32_e32 v6, 16, v12
	v_and_b32_e32 v7, 0xffff0000, v12
	v_lshlrev_b32_e32 v8, 16, v13
	v_and_b32_e32 v9, 0xffff0000, v13
	v_pk_mul_f32 v[6:7], v[16:17], v[6:7] op_sel_hi:[0,1]
	v_pk_mul_f32 v[8:9], v[16:17], v[8:9] op_sel_hi:[0,1]
	s_waitcnt vmcnt(2)
	v_pk_mul_f32 v[2:3], v[6:7], v[204:205]
	v_pk_mul_f32 v[4:5], v[8:9], v[206:207]
	global_store_dwordx4 v[18:19], v[2:5], off offset:32
	v_lshlrev_b32_e32 v6, 16, v14
	v_and_b32_e32 v7, 0xffff0000, v14
	v_lshlrev_b32_e32 v8, 16, v15
	v_and_b32_e32 v9, 0xffff0000, v15
	v_pk_mul_f32 v[6:7], v[16:17], v[6:7] op_sel_hi:[0,1]
	v_pk_mul_f32 v[8:9], v[16:17], v[8:9] op_sel_hi:[0,1]
	s_waitcnt vmcnt(3)
	v_pk_mul_f32 v[2:3], v[6:7], v[208:209]
	v_pk_mul_f32 v[4:5], v[8:9], v[210:211]
	global_store_dwordx4 v[18:19], v[2:5], off offset:48
	s_cbranch_scc1 .LBB0_22
